# attention trim plus XCD-local barriers with arrival issued before the L1 invalidate
# speedup vs baseline: 1.0126x; 1.0023x over previous
; __device__ __forceinline__ unsigned xb_add(unsigned* p, unsigned v) { return __hip_atomic_fetch_add(p, v, __ATOMIC_RELAXED, __HIP_MEMORY_SCOPE_AGENT); }
; #define GSYNC() do { for (int rs_ = 0; rs_ < REP_SYNC; ++rs_) { if (USE_CG) grid.sync(); else xcd_barrier(xbar); } } while (0)
; __device__ __forceinline__ void xcd_barrier(const XcdBarrier& b) {
;     asm volatile("s_waitcnt vmcnt(0)" ::: "memory");
;     __syncthreads();
;     if (threadIdx.x == 0) {
;         unsigned* bar = b.bar;
;         __builtin_amdgcn_s_waitcnt(0);
;         unsigned nloc = b.st[0], nx = b.st[1];
;         if (nloc == 0u) { xcd_barrier_complete(bar, b.x, nloc, nx); b.st[0] = nloc; b.st[1] = nx; }
;         const unsigned old = xb_add(&bar[XB_XSUB(b.x)], 1u);
; __global__ void __launch_bounds__(NTHR) mega_fwd(Args a) {
;     ...
;         { EpiSwiglu E; E.O = ACT; run_gemm(lds, H, 1024, (const bf16_t*)(ws + WS_W13 + f * SZ_W13), 1024, NTOK, 5632, 1024, 1 << 20, 0, E); }
;         GSYNC();
;         { EpiPlain E; E.O = Y1; E.ldc = DM; run_gemm(lds, ACT, DFF, (const bf16_t*)(ws + WS_W2 + f * SZ_W2), DFF, NTOK, 1024, DFF, 1 << 20, 0, E); }
;         GSYNC();
.LBB0_262:
	s_waitcnt vmcnt(0)
	s_barrier
	s_waitcnt vmcnt(0)
	s_barrier
	s_mov_b64 s[0:1], exec
	v_readlane_b32 s2, v249, 10
	v_readlane_b32 s3, v249, 11
	s_and_b64 s[2:3], s[0:1], s[2:3]
	s_mov_b64 exec, s[2:3]
	s_cbranch_execz .LBB0_314
	v_mov_b32_e32 v2, 0x23ffc
	ds_read_b32 v3, v2
	v_readlane_b32 s4, v251, 9
	v_readlane_b32 s5, v251, 10
	s_waitcnt lgkmcnt(0)
	v_readfirstlane_b32 s6, v3
	s_cmp_eq_u32 s6, 0
	s_cbranch_scc1 .Llbfull_314
	s_add_u32 s6, s6, 0xffffcbff
	s_add_u32 s4, s4, s6
	s_addc_u32 s5, s5, -1
	v_mov_b32_e32 v2, 0x23ff8
	ds_read_b32 v3, v2
	v_mov_b32_e32 v5, 0
	v_mov_b32_e32 v6, 1
	global_atomic_add v5, v6, s[4:5]
	buffer_inv sc1
	s_waitcnt lgkmcnt(0)
	v_add_u32_e32 v3, 1, v3
	ds_write_b32 v2, v3
	v_lshlrev_b32_e32 v3, 5, v3

; __device__ __forceinline__ unsigned xb_add(unsigned* p, unsigned v) { return __hip_atomic_fetch_add(p, v, __ATOMIC_RELAXED, __HIP_MEMORY_SCOPE_AGENT); }
; __device__ __forceinline__ void xcd_barrier(const XcdBarrier& b) {
;     asm volatile("s_waitcnt vmcnt(0)" ::: "memory");
;     __syncthreads();
;     if (threadIdx.x == 0) {
;         unsigned* bar = b.bar;
;         __builtin_amdgcn_s_waitcnt(0);
;         unsigned nloc = b.st[0], nx = b.st[1];
;         if (nloc == 0u) { xcd_barrier_complete(bar, b.x, nloc, nx); b.st[0] = nloc; b.st[1] = nx; }
;         const unsigned old = xb_add(&bar[XB_XSUB(b.x)], 1u);
.LBB0_338:
	s_waitcnt vmcnt(0)
	s_barrier
	s_waitcnt vmcnt(0)
	s_barrier
	s_mov_b64 s[0:1], exec
	v_readlane_b32 s2, v249, 10
	v_readlane_b32 s3, v249, 11
	s_and_b64 s[2:3], s[0:1], s[2:3]
	s_mov_b64 exec, s[2:3]
	s_cbranch_execz .LBB0_390
	v_mov_b32_e32 v2, 0x23ffc
	ds_read_b32 v3, v2
	v_readlane_b32 s4, v251, 9
	v_readlane_b32 s5, v251, 10
	s_waitcnt lgkmcnt(0)
	v_readfirstlane_b32 s6, v3
	s_cmp_eq_u32 s6, 0
	s_cbranch_scc1 .Llbfull_390
	s_cmp_eq_u32 s97, 1
	s_cbranch_scc1 .Llbfull_390
	s_add_u32 s6, s6, 0xffffcbff
	s_add_u32 s4, s4, s6
	s_addc_u32 s5, s5, -1
	v_mov_b32_e32 v2, 0x23ff8
	ds_read_b32 v3, v2
	v_mov_b32_e32 v5, 0
	v_mov_b32_e32 v6, 1
	global_atomic_add v5, v6, s[4:5]
	buffer_inv sc1
	s_waitcnt lgkmcnt(0)
	v_add_u32_e32 v3, 1, v3
	ds_write_b32 v2, v3
	v_lshlrev_b32_e32 v3, 5, v3
